# scan: waves 4-7 own all global-load ISSUE / COMMIT work (two elements per thread), waves 0-3 only PREP+P1; merged X+S stage with in-register DPP solve
# speedup vs baseline: 1.0041x; 1.0041x over previous
.LBB0_381:
	s_or_b64 exec, exec, s[2:3]
	s_ashr_i32 s2, s26, 7
	s_lshl_b32 s3, s26, 11
	s_and_b32 s19, s3, 0x3f800
	s_ashr_i32 s3, s2, 31
	s_lshl_b64 s[12:13], s[2:3], 25
	v_readlane_b32 s20, v254, 42
	s_add_u32 s34, s20, s12
	v_readlane_b32 s12, v254, 43
	s_addc_u32 s35, s12, s13
	s_add_u32 s76, s34, 0x4000000
	s_addc_u32 s77, s35, 0
	s_cmpk_lt_u32 s26, 0x80
	s_cselect_b64 s[12:13], -1, 0
	v_add_u32_e32 v184, s19, v101
	s_and_b64 s[20:21], s[12:13], exec
	v_lshl_or_b32 v183, v184, 6, v109
	s_cselect_b32 s19, 0, 0x7f0
	v_lshl_add_u32 v194, s19, 6, v183
	v_lshlrev_b64 v[0:1], 1, v[194:195]
	v_lshl_add_u64 v[2:3], s[44:45], 0, v[0:1]
	global_load_dword v8, v[2:3], off
	v_lshl_add_u64 v[2:3], s[42:43], 0, v[0:1]
	global_load_dword v4, v[2:3], off
	v_lshl_add_u64 v[2:3], s[0:1], 0, v[0:1]
	global_load_dword v9, v[2:3], off
	v_lshl_add_u64 v[2:3], s[34:35], 0, v[0:1]
	v_lshl_add_u64 v[0:1], s[76:77], 0, v[0:1]
	v_add_u32_e32 v194, s19, v184
	global_load_dword v14, v[2:3], off
	global_load_dword v5, v[0:1], off
	v_lshl_add_u64 v[0:1], v[194:195], 2, s[40:41]
	global_load_dword v0, v[0:1], off
	v_cndmask_b32_e64 v18, v111, v101, s[12:13]
	s_movk_i32 s19, 0x600
	v_mad_u64_u32 v[106:107], s[20:21], v18, s19, v[100:101]
	s_cselect_b32 s19, 16, 0x7e0
	v_lshl_add_u32 v194, s19, 6, v183
	v_add_u32_e32 v107, 0x6000, v106
	v_add_u32_e32 v185, v142, v153
	v_add_u32_e32 v186, v141, v154
	v_add_u32_e32 v187, v138, v155
	v_add_u32_e32 v188, v140, v155
	s_waitcnt vmcnt(4)
	v_lshlrev_b32_e32 v2, 16, v4
	v_and_b32_e32 v3, 0xffff0000, v4
	v_pk_mul_f32 v[6:7], v[102:103], v[2:3]
	s_waitcnt vmcnt(1)
	v_lshlrev_b32_e32 v4, 16, v5
	v_and_b32_e32 v5, 0xffff0000, v5
	s_waitcnt vmcnt(0)
	v_pk_mul_f32 v[0:1], v[6:7], v[0:1] op_sel_hi:[1,0]
	v_lshlrev_b32_e32 v6, 16, v14
	v_and_b32_e32 v7, 0xffff0000, v14
	ds_write2_b64 v106, v[0:1], v[6:7] offset1:32
	v_pk_add_f32 v[6:7], v[4:5], -1.0 op_sel_hi:[1,0]
	v_pk_mul_f32 v[0:1], v[4:5], v[0:1] neg_lo:[0,1] neg_hi:[0,1]
	v_pk_fma_f32 v[6:7], v[104:105], v[6:7], 1.0 op_sel_hi:[1,1,0]
	s_nop 0
	v_pk_mul_f32 v[2:3], v[6:7], v[2:3]
	ds_write2_b64 v106, v[2:3], v[0:1] offset0:64 offset1:96
	v_lshlrev_b32_e32 v0, 16, v8
	v_and_b32_e32 v1, 0xffff0000, v8
	v_lshlrev_b32_e32 v2, 16, v9
	v_and_b32_e32 v3, 0xffff0000, v9
	ds_write2_b64 v106, v[0:1], v[2:3] offset0:128 offset1:160
	v_lshlrev_b64 v[0:1], 1, v[194:195]
	v_lshl_add_u64 v[2:3], s[44:45], 0, v[0:1]
	global_load_dword v8, v[2:3], off
	v_lshl_add_u64 v[2:3], s[42:43], 0, v[0:1]
	global_load_dword v4, v[2:3], off
	v_lshl_add_u64 v[2:3], s[0:1], 0, v[0:1]
	global_load_dword v9, v[2:3], off
	v_lshl_add_u64 v[2:3], s[34:35], 0, v[0:1]
	v_lshl_add_u64 v[0:1], s[76:77], 0, v[0:1]
	v_add_u32_e32 v194, s19, v184
	global_load_dword v14, v[2:3], off
	global_load_dword v5, v[0:1], off
	v_lshl_add_u64 v[0:1], v[194:195], 2, s[40:41]
	global_load_dword v0, v[0:1], off
	s_cselect_b32 s19, 32, 0x7d0
	v_lshl_add_u32 v194, s19, 6, v183
	s_waitcnt vmcnt(4)
	v_lshlrev_b32_e32 v2, 16, v4
	v_and_b32_e32 v3, 0xffff0000, v4
	v_pk_mul_f32 v[6:7], v[102:103], v[2:3]
	s_waitcnt vmcnt(1)
	v_lshlrev_b32_e32 v4, 16, v5
	v_and_b32_e32 v5, 0xffff0000, v5
	s_waitcnt vmcnt(0)
	v_pk_mul_f32 v[0:1], v[6:7], v[0:1] op_sel_hi:[1,0]
	v_lshlrev_b32_e32 v6, 16, v14
	v_and_b32_e32 v7, 0xffff0000, v14
	ds_write2_b64 v107, v[0:1], v[6:7] offset1:32
	v_pk_add_f32 v[6:7], v[4:5], -1.0 op_sel_hi:[1,0]
	v_pk_mul_f32 v[0:1], v[4:5], v[0:1] neg_lo:[0,1] neg_hi:[0,1]
	v_pk_fma_f32 v[6:7], v[104:105], v[6:7], 1.0 op_sel_hi:[1,1,0]
	v_lshlrev_b64 v[4:5], 1, v[194:195]
	v_pk_mul_f32 v[2:3], v[6:7], v[2:3]
	ds_write2_b64 v107, v[2:3], v[0:1] offset0:64 offset1:96
	v_lshlrev_b32_e32 v0, 16, v8
	v_and_b32_e32 v1, 0xffff0000, v8
	v_lshlrev_b32_e32 v2, 16, v9
	v_and_b32_e32 v3, 0xffff0000, v9
	ds_write2_b64 v107, v[0:1], v[2:3] offset0:128 offset1:160
	v_lshl_add_u64 v[0:1], s[44:45], 0, v[4:5]
	v_lshl_add_u64 v[2:3], s[42:43], 0, v[4:5]
	global_load_dword v0, v[0:1], off
	v_lshl_add_u64 v[6:7], s[34:35], 0, v[4:5]
	global_load_dword v1, v[2:3], off
	v_lshl_add_u64 v[2:3], s[0:1], 0, v[4:5]
	v_lshl_add_u64 v[4:5], s[76:77], 0, v[4:5]
	v_add_u32_e32 v194, s19, v184
	s_cselect_b32 s19, 48, 0x7c0
	global_load_dword v2, v[2:3], off
	s_nop 0
	global_load_dword v4, v[4:5], off
	s_nop 0
	global_load_dword v3, v[6:7], off
	v_lshl_add_u64 v[6:7], v[194:195], 2, s[40:41]
	v_lshl_add_u32 v194, s19, 6, v183
	v_lshlrev_b64 v[14:15], 1, v[194:195]
	global_load_dword v108, v[6:7], off
	v_lshl_add_u64 v[6:7], s[44:45], 0, v[14:15]
	global_load_dword v5, v[6:7], off
	v_lshl_add_u64 v[6:7], s[42:43], 0, v[14:15]
	v_lshl_add_u64 v[8:9], s[0:1], 0, v[14:15]
	global_load_dword v6, v[6:7], off
	v_add_u32_e32 v194, s19, v184
	global_load_dword v7, v[8:9], off
	v_lshl_add_u64 v[8:9], s[34:35], 0, v[14:15]
	v_lshl_add_u64 v[14:15], s[76:77], 0, v[14:15]
	global_load_dword v8, v[8:9], off
	s_nop 0
	global_load_dword v9, v[14:15], off
	v_lshl_add_u64 v[14:15], v[194:195], 2, s[40:41]
	global_load_dword v110, v[14:15], off
	s_and_b64 s[98:99], s[12:13], exec
	s_movk_i32 s98, 0x7d0
	s_cselect_b32 s98, 32, s98
	v_lshl_add_u32 v194, s98, 6, v183
	v_lshlrev_b32_e32 v194, 1, v194
	global_load_dword v201, v194, s[44:45] offset:-1024
	global_load_dword v202, v194, s[42:43] offset:-1024
	global_load_dword v203, v194, s[0:1] offset:-1024
	global_load_dword v204, v194, s[34:35] offset:-1024
	global_load_dword v205, v194, s[76:77] offset:-1024
	v_add_u32_e32 v206, s98, v184
	v_lshlrev_b32_e32 v206, 2, v206
	global_load_dword v206, v206, s[40:41] offset:-32
	s_movk_i32 s98, 0x7c0
	s_cselect_b32 s98, 48, s98
	v_lshl_add_u32 v194, s98, 6, v183
	v_lshlrev_b32_e32 v194, 1, v194
	global_load_dword v207, v194, s[44:45] offset:-1024
	global_load_dword v208, v194, s[42:43] offset:-1024
	global_load_dword v209, v194, s[0:1] offset:-1024
	global_load_dword v210, v194, s[34:35] offset:-1024
	global_load_dword v211, v194, s[76:77] offset:-1024
	v_add_u32_e32 v212, s98, v184
	v_lshlrev_b32_e32 v212, 2, v212
	global_load_dword v212, v212, s[40:41] offset:-32
	s_waitcnt lgkmcnt(0)
	s_barrier
	s_mov_b64 s[74:75], exec
	v_readlane_b32 s20, v254, 50
	v_readlane_b32 s21, v254, 51
	s_and_b64 s[20:21], s[74:75], s[20:21]
	s_mov_b64 exec, s[20:21]
	s_cbranch_execz .LBB0_384
	ds_read2st64_b32 v[14:15], v142 offset0:1 offset1:7
	ds_read2st64_b32 v[16:17], v142 offset0:13 offset1:19
	ds_read2st64_b32 v[20:21], v142 offset0:25 offset1:31
	ds_read2st64_b32 v[22:23], v142 offset0:37 offset1:43
	ds_read2st64_b32 v[24:25], v142 offset0:49 offset1:55
	ds_read2st64_b32 v[26:27], v142 offset0:61 offset1:67
	ds_read2st64_b32 v[28:29], v142 offset0:73 offset1:79
	ds_read_b32 v19, v142 offset:21760
	ds_read2st64_b32 v[30:31], v185 offset1:1
	ds_read2st64_b32 v[32:33], v185 offset0:2 offset1:3
	ds_read2st64_b32 v[34:35], v185 offset0:4 offset1:5
	s_waitcnt lgkmcnt(10)
	v_add_f32_e32 v14, 0, v14
	v_cndmask_b32_e64 v36, v14, 0, s[48:49]
	v_cndmask_b32_e64 v37, 0, v15, s[60:61]
	v_add_f32_e32 v14, v14, v15
	v_add_f32_e32 v36, v36, v37
	s_waitcnt lgkmcnt(9)
	v_cndmask_b32_e64 v37, 0, v16, s[62:63]
	v_add_f32_e32 v14, v14, v16
	v_add_f32_e32 v36, v36, v37
	v_cndmask_b32_e64 v37, 0, v17, s[56:57]
	v_add_f32_e32 v14, v14, v17
	v_add_f32_e32 v36, v36, v37
	s_waitcnt lgkmcnt(8)
	v_cndmask_b32_e64 v37, 0, v20, s[64:65]
	v_readlane_b32 s20, v254, 52
	v_add_f32_e32 v14, v14, v20
	v_add_f32_e32 v36, v36, v37
	v_cndmask_b32_e64 v37, 0, v21, s[66:67]
	v_readlane_b32 s21, v254, 53
	v_add_f32_e32 v14, v14, v21
	v_add_f32_e32 v36, v36, v37
	s_waitcnt lgkmcnt(7)
	v_cndmask_b32_e64 v37, 0, v22, s[20:21]
	v_add_f32_e32 v14, v14, v22
	v_readlane_b32 s24, v254, 54
	v_add_f32_e32 v36, v36, v37
	v_add_f32_e32 v14, v14, v23
	s_waitcnt lgkmcnt(6)
	v_cndmask_b32_e64 v15, v24, 0, s[48:49]
	v_readlane_b32 s25, v254, 55
	v_add_f32_e32 v36, 0, v36
	v_add_f32_e32 v14, v14, v15
	v_cndmask_b32_e64 v15, 0, v25, s[24:25]
	v_readlane_b32 s24, v254, 56
	v_mul_f32_e32 v37, 0xbfb8aa3b, v36
	s_waitcnt lgkmcnt(2)
	v_add_f32_e32 v31, v36, v31
	v_readlane_b32 s25, v254, 57
	v_exp_f32_e32 v37, v37
	v_mul_f32_e32 v36, 0xbfb8aa3b, v31
	v_mul_f32_e32 v31, 0x3fb8aa3b, v31
	v_add_f32_e32 v14, v14, v15
	v_cndmask_b32_e64 v15, 0, v26, s[24:25]
	v_readlane_b32 s24, v254, 58
	v_exp_f32_e32 v31, v31
	v_exp_f32_e32 v36, v36
	v_readlane_b32 s25, v254, 59
	v_add_f32_e32 v14, v14, v15
	v_mul_f32_e32 v30, v37, v30
	v_cndmask_b32_e64 v15, 0, v27, s[24:25]
	v_readlane_b32 s24, v254, 60
	v_readlane_b32 s25, v254, 61
	v_add_f32_e32 v14, v14, v15
	v_cvt_pk_bf16_f32 v30, v30, v195
	s_waitcnt lgkmcnt(1)
	v_mul_f32_e32 v33, v33, v31
	v_cndmask_b32_e64 v15, 0, v28, s[24:25]
	v_readlane_b32 s24, v254, 62
	v_mul_f32_e32 v31, v32, v31
	s_waitcnt lgkmcnt(0)
	v_mul_f32_e32 v32, v34, v36
	v_readlane_b32 s25, v254, 63
	v_cvt_pk_bf16_f32 v33, v33, v195
	v_cvt_pk_bf16_f32 v31, v31, v195
	v_cvt_pk_bf16_f32 v32, v32, v195
	v_cvt_pk_bf16_f32 v34, v35, v195
	ds_write_b16 v186, v30 offset:49152
	ds_write_b16 v186, v33 offset:53760
	ds_write_b16 v186, v31 offset:56064
	ds_write_b16 v186, v32 offset:58368
	ds_write_b16 v187, v33 offset:62976
	ds_write_b16 v187, v31 offset:63008
	ds_write_b16 v188, v34 offset:32
	v_add_f32_e32 v14, v14, v15
	v_cndmask_b32_e64 v15, 0, v29, s[24:25]
	v_readlane_b32 s24, v255, 0
	ds_read2st64_b32 v[30:31], v169 offset1:1
	ds_read2st64_b32 v[32:33], v169 offset0:2 offset1:3
	ds_read2st64_b32 v[34:35], v169 offset0:4 offset1:5
	v_readlane_b32 s25, v255, 1
	v_add_f32_e32 v14, v14, v15
	s_waitcnt lgkmcnt(0)
	v_cvt_pk_bf16_f32 v20, v35, v195
	v_cndmask_b32_e64 v15, 0, v19, s[24:25]
	v_add_f32_e32 v14, v14, v15
	v_mul_f32_e32 v15, 0xbfb8aa3b, v14
	v_add_f32_e32 v14, v14, v31
	v_exp_f32_e32 v15, v15
	v_mul_f32_e32 v16, 0xbfb8aa3b, v14
	v_mul_f32_e32 v14, 0x3fb8aa3b, v14
	v_exp_f32_e32 v17, v14
	v_exp_f32_e32 v14, v16
	v_mul_f32_e32 v15, v15, v30
	v_cvt_pk_bf16_f32 v15, v15, v195
	v_mul_f32_e32 v16, v33, v17
	v_mul_f32_e32 v17, v32, v17
	v_mul_f32_e32 v19, v34, v14
	v_cvt_pk_bf16_f32 v16, v16, v195
	v_cvt_pk_bf16_f32 v17, v17, v195
	v_cvt_pk_bf16_f32 v19, v19, v195
	ds_write_b16 v171, v15 offset:49152
	ds_write_b16 v171, v16 offset:53760
	ds_write_b16 v171, v17 offset:56064
	ds_write_b16 v171, v19 offset:58368
	v_add_u32_e32 v15, v138, v158
	ds_write_b16 v15, v16 offset:62976
	ds_write_b16 v15, v17 offset:63008
	v_add_u32_e32 v15, v140, v158
	ds_write_b16 v15, v20 offset:32
	s_and_b64 exec, exec, s[20:21]
	v_add_u32_e32 v15, 0x18d00, v159
	ds_write_b32 v15, v14

.Lsx0_c:
	s_or_b64 exec, exec, s[2:3]
	v_mov_b32_e32 v22, 0
	v_mov_b32_e32 v23, 0
	v_mov_b32_e32 v24, 0
	v_mov_b32_e32 v25, 0
	s_and_saveexec_b64 s[2:3], s[56:57]
	s_cbranch_execz .LBB0_403
	ds_read_b128 v[48:51], v174
	ds_read_b128 v[60:63], v192 offset:49152
	ds_read_b128 v[52:55], v174 offset:64
	ds_read_b128 v[64:67], v192 offset:49216
	ds_read_b128 v[56:59], v175
	ds_read_b128 v[68:71], v199
	ds_read_b128 v[72:75], v192 offset:58368
	ds_read_b128 v[76:79], v192 offset:58432
	ds_read_b128 v[80:83], v151
	ds_read_b128 v[84:87], v151 offset:16
	ds_read_b128 v[88:91], v151 offset:32
	ds_read_b128 v[92:95], v151 offset:48
	s_cmp_gt_u32 s36, 62
	s_cbranch_scc1 .Lcp0
	s_waitcnt vmcnt(0)
	v_lshlrev_b32_e32 v136, 16, v1
	v_and_b32_e32 v137, 0xffff0000, v1
	v_pk_mul_f32 v[124:125], v[102:103], v[136:137]
	v_lshlrev_b32_e32 v126, 16, v3
	v_pk_mul_f32 v[124:125], v[108:109], v[124:125] op_sel_hi:[0,1]
	v_and_b32_e32 v127, 0xffff0000, v3
	v_lshlrev_b32_e32 v130, 16, v4
	v_and_b32_e32 v131, 0xffff0000, v4
	v_pk_add_f32 v[128:129], v[130:131], -1.0 op_sel_hi:[1,0]
	v_pk_mul_f32 v[130:131], v[130:131], v[124:125] neg_lo:[0,1] neg_hi:[0,1]
	v_pk_fma_f32 v[128:129], v[104:105], v[128:129], 1.0 op_sel_hi:[1,1,0]
	s_nop 0
	v_pk_mul_f32 v[128:129], v[128:129], v[136:137]
	v_lshlrev_b32_e32 v132, 16, v0
	v_and_b32_e32 v133, 0xffff0000, v0
	v_lshlrev_b32_e32 v134, 16, v2
	v_and_b32_e32 v135, 0xffff0000, v2
	v_lshlrev_b32_e32 v136, 16, v202
	v_and_b32_e32 v137, 0xffff0000, v202
	v_pk_mul_f32 v[214:215], v[102:103], v[136:137]
	v_lshlrev_b32_e32 v216, 16, v204
	v_pk_mul_f32 v[214:215], v[206:207], v[214:215] op_sel_hi:[0,1]
	v_and_b32_e32 v217, 0xffff0000, v204
	v_lshlrev_b32_e32 v228, 16, v205
	v_and_b32_e32 v229, 0xffff0000, v205
	v_pk_add_f32 v[218:219], v[228:229], -1.0 op_sel_hi:[1,0]
	v_pk_mul_f32 v[228:229], v[228:229], v[214:215] neg_lo:[0,1] neg_hi:[0,1]
	v_pk_fma_f32 v[218:219], v[104:105], v[218:219], 1.0 op_sel_hi:[1,1,0]
	s_nop 0
	v_pk_mul_f32 v[218:219], v[218:219], v[136:137]
	v_lshlrev_b32_e32 v230, 16, v201
	v_and_b32_e32 v231, 0xffff0000, v201
	v_lshlrev_b32_e32 v232, 16, v203
	v_and_b32_e32 v233, 0xffff0000, v203
.Lcp0:
	s_waitcnt lgkmcnt(10)
	v_mfma_f32_16x16x32_bf16 v[30:33], v[48:51], v[60:63], 0
	s_waitcnt lgkmcnt(8)
	v_mfma_f32_16x16x32_bf16 v[30:33], v[52:55], v[64:67], v[30:33]
	s_waitcnt lgkmcnt(6)
	v_mfma_f32_16x16x32_bf16 v[30:33], v[56:59], v[68:71], v[30:33]
	s_waitcnt lgkmcnt(5)
	v_mfma_f32_16x16x32_bf16 v[22:25], v[48:51], v[72:75], 0
	s_waitcnt lgkmcnt(4)
	v_mfma_f32_16x16x32_bf16 v[22:25], v[52:55], v[76:79], v[22:25]
	s_cmp_eq_u32 s36, 0
	s_cbranch_scc1 .Lis0b
	s_cmp_gt_u32 s36, 62
	s_cbranch_scc1 .Lis0b
	s_add_i32 s24, s19, 0xffffffc0
	s_add_i32 s25, s21, 0x30
	s_and_b64 s[98:99], s[12:13], exec
	s_cselect_b32 s24, s25, s24
	v_lshl_add_u32 v194, s24, 6, v183
	v_lshlrev_b32_e32 v112, 1, v194
	global_load_dword v5, v112, s[44:45]
	global_load_dword v207, v112, s[44:45] offset:-1024
	global_load_dword v6, v112, s[42:43]
	global_load_dword v208, v112, s[42:43] offset:-1024
	global_load_dword v7, v112, s[0:1]
	global_load_dword v209, v112, s[0:1] offset:-1024
	global_load_dword v8, v112, s[34:35]
	global_load_dword v210, v112, s[34:35] offset:-1024
	global_load_dword v9, v112, s[76:77]
	global_load_dword v211, v112, s[76:77] offset:-1024
	v_add_u32_e32 v194, s24, v184
	v_lshlrev_b32_e32 v114, 2, v194
	global_load_dword v110, v114, s[40:41]
	global_load_dword v212, v114, s[40:41] offset:-32

.LBB0_422:
	s_or_b64 exec, exec, s[2:3]
	s_cmp_lt_u32 s36, 63
	s_cselect_b64 vcc, -1, 0
	s_cmp_gt_u32 s36, 62
	s_cbranch_scc1 .LBB0_424
	s_and_b64 s[98:99], s[56:57], exec
	s_cbranch_scc0 .LBB0_424
	ds_write2_b64 v106, v[124:125], v[126:127] offset1:32
	ds_write2_b64 v106, v[128:129], v[130:131] offset0:64 offset1:96
	ds_write2_b64 v106, v[132:133], v[134:135] offset0:128 offset1:160
	s_and_b64 s[98:99], s[12:13], exec
	s_movk_i32 s98, 0x3000
	s_cselect_b32 s98, 0xffffd000, s98
	v_add_u32_e32 v136, s98, v106
	ds_write2_b64 v136, v[214:215], v[216:217] offset1:32
	ds_write2_b64 v136, v[218:219], v[228:229] offset0:64 offset1:96
	ds_write2_b64 v136, v[230:231], v[232:233] offset0:128 offset1:160
.LBB0_424:
.LBB0_426:
	s_add_i32 s24, s19, -16
	s_and_b64 s[2:3], s[12:13], exec
	s_waitcnt lgkmcnt(0)
	s_barrier
	s_cselect_b32 s2, s21, s24
	s_cmpk_lt_u32 s20, 0x7f
	ds_read_b64 v[236:237], v190
	v_lshl_add_u32 v194, s2, 6, v183
	s_cselect_b64 s[2:3], -1, 0
	v_lshl_add_u64 v[238:239], v[194:195], 1, s[78:79]
	s_and_b64 s[68:69], s[54:55], s[2:3]
	s_and_saveexec_b64 s[74:75], s[54:55]
	s_cbranch_execz .Lsx1_c
	s_waitcnt lgkmcnt(0)
	v_cvt_pk_bf16_f32 v240, v236, v237
	global_store_dword v[238:239], v240, off
.Lsx1_c:
	s_or_b64 exec, exec, s[74:75]
	v_mov_b32_e32 v22, 0
	v_mov_b32_e32 v23, 0
	v_mov_b32_e32 v24, 0
	v_mov_b32_e32 v25, 0
	s_and_saveexec_b64 s[74:75], s[56:57]
	s_cbranch_execz .LBB0_432
	ds_read_b128 v[48:51], v174
	ds_read_b128 v[60:63], v192 offset:51456
	ds_read_b128 v[52:55], v174 offset:64
	ds_read_b128 v[64:67], v192 offset:51520
	ds_read_b128 v[56:59], v175 offset:5120
	ds_read_b128 v[68:71], v199
	ds_read_b128 v[72:75], v192 offset:60672
	ds_read_b128 v[76:79], v192 offset:60736
	ds_read_b128 v[80:83], v151
	ds_read_b128 v[84:87], v151 offset:16
	ds_read_b128 v[88:91], v151 offset:32
	ds_read_b128 v[92:95], v151 offset:48
	s_cmp_gt_u32 s36, 62
	s_cbranch_scc1 .Lcp1
	s_waitcnt vmcnt(0)
	v_lshlrev_b32_e32 v136, 16, v6
	v_and_b32_e32 v137, 0xffff0000, v6
	v_pk_mul_f32 v[124:125], v[102:103], v[136:137]
	v_lshlrev_b32_e32 v126, 16, v8
	v_pk_mul_f32 v[124:125], v[110:111], v[124:125] op_sel_hi:[0,1]
	v_and_b32_e32 v127, 0xffff0000, v8
	v_lshlrev_b32_e32 v130, 16, v9
	v_and_b32_e32 v131, 0xffff0000, v9
	v_pk_add_f32 v[128:129], v[130:131], -1.0 op_sel_hi:[1,0]
	v_pk_mul_f32 v[130:131], v[130:131], v[124:125] neg_lo:[0,1] neg_hi:[0,1]
	v_pk_fma_f32 v[128:129], v[104:105], v[128:129], 1.0 op_sel_hi:[1,1,0]
	s_nop 0
	v_pk_mul_f32 v[128:129], v[128:129], v[136:137]
	v_lshlrev_b32_e32 v132, 16, v5
	v_and_b32_e32 v133, 0xffff0000, v5
	v_lshlrev_b32_e32 v134, 16, v7
	v_and_b32_e32 v135, 0xffff0000, v7
	v_lshlrev_b32_e32 v136, 16, v208
	v_and_b32_e32 v137, 0xffff0000, v208
	v_pk_mul_f32 v[214:215], v[102:103], v[136:137]
	v_lshlrev_b32_e32 v216, 16, v210
	v_pk_mul_f32 v[214:215], v[212:213], v[214:215] op_sel_hi:[0,1]
	v_and_b32_e32 v217, 0xffff0000, v210
	v_lshlrev_b32_e32 v228, 16, v211
	v_and_b32_e32 v229, 0xffff0000, v211
	v_pk_add_f32 v[218:219], v[228:229], -1.0 op_sel_hi:[1,0]
	v_pk_mul_f32 v[228:229], v[228:229], v[214:215] neg_lo:[0,1] neg_hi:[0,1]
	v_pk_fma_f32 v[218:219], v[104:105], v[218:219], 1.0 op_sel_hi:[1,1,0]
	s_nop 0
	v_pk_mul_f32 v[218:219], v[218:219], v[136:137]
	v_lshlrev_b32_e32 v230, 16, v207
	v_and_b32_e32 v231, 0xffff0000, v207
	v_lshlrev_b32_e32 v232, 16, v209
	v_and_b32_e32 v233, 0xffff0000, v209
.Lcp1:
	s_waitcnt lgkmcnt(10)
	v_mfma_f32_16x16x32_bf16 v[30:33], v[48:51], v[60:63], 0
	s_waitcnt lgkmcnt(8)
	v_mfma_f32_16x16x32_bf16 v[30:33], v[52:55], v[64:67], v[30:33]
	s_waitcnt lgkmcnt(6)
	v_mfma_f32_16x16x32_bf16 v[30:33], v[56:59], v[68:71], v[30:33]
	s_waitcnt lgkmcnt(5)
	v_mfma_f32_16x16x32_bf16 v[22:25], v[48:51], v[72:75], 0
	s_waitcnt lgkmcnt(4)
	v_mfma_f32_16x16x32_bf16 v[22:25], v[52:55], v[76:79], v[22:25]
	s_cmp_gt_u32 s36, 61
	s_cbranch_scc1 .Lis1bw
	s_add_i32 s24, s19, 0xffffffb0
	s_add_i32 s25, s21, 64
	s_and_b64 s[98:99], s[12:13], exec
	s_cselect_b32 s24, s25, s24
	v_lshl_add_u32 v194, s24, 6, v183
	v_lshlrev_b32_e32 v112, 1, v194
	global_load_dword v0, v112, s[44:45]
	global_load_dword v201, v112, s[44:45] offset:-1024
	global_load_dword v1, v112, s[42:43]
	global_load_dword v202, v112, s[42:43] offset:-1024
	global_load_dword v2, v112, s[0:1]
	global_load_dword v203, v112, s[0:1] offset:-1024
	global_load_dword v4, v112, s[76:77]
	global_load_dword v205, v112, s[76:77] offset:-1024
	global_load_dword v3, v112, s[34:35]
	global_load_dword v204, v112, s[34:35] offset:-1024
	v_add_u32_e32 v194, s24, v184
	v_lshlrev_b32_e32 v114, 2, v194
	global_load_dword v108, v114, s[40:41]
	global_load_dword v206, v114, s[40:41] offset:-32
	s_branch .Lis1b

.LBB0_451:
	s_or_b64 exec, exec, s[2:3]
	s_andn2_b64 vcc, exec, vcc
	s_cbranch_vccnz .LBB0_453
	s_and_b64 s[98:99], s[56:57], exec
	s_cbranch_scc0 .LBB0_453
	ds_write2_b64 v107, v[124:125], v[126:127] offset1:32
	ds_write2_b64 v107, v[128:129], v[130:131] offset0:64 offset1:96
	ds_write2_b64 v107, v[132:133], v[134:135] offset0:128 offset1:160
	s_and_b64 s[98:99], s[12:13], exec
	s_movk_i32 s98, 0x3000
	s_cselect_b32 s98, 0xffffd000, s98
	v_add_u32_e32 v136, s98, v107
	ds_write2_b64 v136, v[214:215], v[216:217] offset1:32
	ds_write2_b64 v136, v[218:219], v[228:229] offset0:64 offset1:96
	ds_write2_b64 v136, v[230:231], v[232:233] offset0:128 offset1:160
